# v41 plus diff-attn M heads reordered so the K-fragment ds_reads issue before the V-address and first-tile flag computations
# baseline (speedup 1.0000x reference)
.LBB0_1150:
	s_add_i32 s95, s94, -3
	s_add_i32 s98, s99, 0x2400
	s_cmp_eq_u32 s98, 0x6c00
	s_cselect_b32 s98, 0, s98
	v_add_u32_e32 v84, s98, v218
	ds_read_b128 v[80:83], v84
	ds_read_b128 v[224:227], v84 offset:4608
	ds_read_b128 v[220:223], v84 offset:32
	ds_read_b128 v[228:231], v84 offset:4640
	ds_read_b128 v[192:195], v84 offset:64
	ds_read_b128 v[196:199], v84 offset:4672
	ds_read_b128 v[184:187], v84 offset:96
	ds_read_b128 v[188:191], v84 offset:4704
	s_add_i32 s1, s51, 0xc000
	s_and_b32 s96, s1, 0xc000
	v_add_u32_e32 v236, s96, v217
	s_cmp_eq_u32 s51, 0
	s_cselect_b64 s[72:73], -1, 0
	ds_read_b64_tr_b16 v[164:165], v236 offset:0
	ds_read_b64_tr_b16 v[166:167], v236 offset:0x800
	ds_read_b64_tr_b16 v[160:161], v236 offset:0x1000
	ds_read_b64_tr_b16 v[162:163], v236 offset:0x1800
	ds_read_b64_tr_b16 v[156:157], v236 offset:0x2000
	ds_read_b64_tr_b16 v[158:159], v236 offset:0x2800
	ds_read_b64_tr_b16 v[152:153], v236 offset:0x3000
	ds_read_b64_tr_b16 v[154:155], v236 offset:0x3800
	s_waitcnt lgkmcnt(15)
	v_mfma_f32_32x32x16_bf16 v[96:111], v[80:83], v[112:115], v[64:79]
	s_waitcnt lgkmcnt(14)
	v_mfma_f32_32x32x16_bf16 v[80:95], v[224:227], v[112:115], v[64:79]
	s_waitcnt lgkmcnt(13)
	v_mfma_f32_32x32x16_bf16 v[96:111], v[220:223], v[116:119], v[96:111]
	s_waitcnt lgkmcnt(12)
	v_mfma_f32_32x32x16_bf16 v[80:95], v[228:231], v[116:119], v[80:95]
	s_waitcnt lgkmcnt(8)
	ds_read_b64_tr_b16 v[220:221], v236 offset:0x200
	ds_read_b64_tr_b16 v[222:223], v236 offset:0xa00
	ds_read_b64_tr_b16 v[224:225], v236 offset:0x1200
	ds_read_b64_tr_b16 v[226:227], v236 offset:0x1a00
	ds_read_b64_tr_b16 v[228:229], v236 offset:0x2200
	ds_read_b64_tr_b16 v[230:231], v236 offset:0x2a00
	ds_read_b64_tr_b16 v[232:233], v236 offset:0x3200
	ds_read_b64_tr_b16 v[234:235], v236 offset:0x3a00
	v_mfma_f32_32x32x16_bf16 v[96:111], v[192:195], v[120:123], v[96:111]
	v_mfma_f32_32x32x16_bf16 v[80:95], v[196:199], v[120:123], v[80:95]
	v_mfma_f32_32x32x16_bf16 v[96:111], v[184:187], v[124:127], v[96:111]
	v_mfma_f32_32x32x16_bf16 v[80:95], v[188:191], v[124:127], v[80:95]
	ds_read_b64_tr_b16 v[184:185], v236 offset:0x600
	ds_read_b64_tr_b16 v[186:187], v236 offset:0xe00
	ds_read_b64_tr_b16 v[188:189], v236 offset:0x1600
	ds_read_b64_tr_b16 v[190:191], v236 offset:0x1e00
	ds_read_b64_tr_b16 v[192:193], v236 offset:0x2600
	ds_read_b64_tr_b16 v[194:195], v236 offset:0x2e00
	ds_read_b64_tr_b16 v[196:197], v236 offset:0x3600
	ds_read_b64_tr_b16 v[198:199], v236 offset:0x3e00
	s_and_b64 vcc, exec, s[72:73]
	s_cbranch_vccnz .Ld1_a_nopv
	s_waitcnt lgkmcnt(15)
	v_mfma_f32_32x32x16_bf16 v[48:63], v[180:183], v[164:167], v[48:63]
	v_mfma_f32_32x32x16_bf16 v[48:63], v[176:179], v[160:163], v[48:63]
	v_mfma_f32_32x32x16_bf16 v[48:63], v[172:175], v[156:159], v[48:63]
	v_mfma_f32_32x32x16_bf16 v[48:63], v[168:171], v[152:155], v[48:63]
	ds_read_b64_tr_b16 v[164:165], v236 offset:0x400
	ds_read_b64_tr_b16 v[166:167], v236 offset:0xc00
	ds_read_b64_tr_b16 v[160:161], v236 offset:0x1400
	ds_read_b64_tr_b16 v[162:163], v236 offset:0x1c00
	ds_read_b64_tr_b16 v[156:157], v236 offset:0x2400
	ds_read_b64_tr_b16 v[158:159], v236 offset:0x2c00
	ds_read_b64_tr_b16 v[152:153], v236 offset:0x3400
	ds_read_b64_tr_b16 v[154:155], v236 offset:0x3c00
	s_waitcnt lgkmcnt(15)
	v_mfma_f32_32x32x16_bf16 v[32:47], v[180:183], v[220:223], v[32:47]
	v_mfma_f32_32x32x16_bf16 v[32:47], v[176:179], v[224:227], v[32:47]
	v_mfma_f32_32x32x16_bf16 v[32:47], v[172:175], v[228:231], v[32:47]
	v_mfma_f32_32x32x16_bf16 v[32:47], v[168:171], v[232:235], v[32:47]
	s_waitcnt lgkmcnt(8)
	v_mfma_f32_32x32x16_bf16 v[0:15], v[180:183], v[184:187], v[0:15]
	v_mfma_f32_32x32x16_bf16 v[0:15], v[176:179], v[188:191], v[0:15]
	v_mfma_f32_32x32x16_bf16 v[0:15], v[172:175], v[192:195], v[0:15]
	v_mfma_f32_32x32x16_bf16 v[0:15], v[168:171], v[196:199], v[0:15]
	s_waitcnt lgkmcnt(0)
	v_mfma_f32_32x32x16_bf16 v[16:31], v[180:183], v[164:167], v[16:31]
	v_mfma_f32_32x32x16_bf16 v[16:31], v[176:179], v[160:163], v[16:31]
	v_mfma_f32_32x32x16_bf16 v[16:31], v[172:175], v[156:159], v[16:31]
	v_mfma_f32_32x32x16_bf16 v[16:31], v[168:171], v[152:155], v[16:31]

; #define SBAR() __builtin_amdgcn_sched_barrier(0)
; __device__ __forceinline__ float max3f(float a, float b, float c) { return __builtin_fmaxf(__builtin_fmaxf(a, b), c); }
; #define SWAIT() asm volatile("s_waitcnt vmcnt(3)" ::: "memory")
; #define VSEG(j) do { rowmax_adjust(S0, S1, m2, negm, alpha, (j) == 0); RESC(alpha); l_reg = l_reg * alpha + exp_pack(S0, S1, pa0, pa1, pa2, pa3); } while (0)
; __device__ __forceinline__ void rowmax_adjust(f32x16& p0, f32x16& p1, float& m2, f32x16& negm, float& alpha, const bool first) {
;     constexpr float THR2 = THR * 1.4426950408889634f;
;     float pmax = max3f(p0[0], p0[1], p0[2]);
; #pragma unroll
;     for (int r = 3; r < 15; r += 2) pmax = max3f(pmax, p0[r], p0[r + 1]);
;     pmax = max3f(pmax, p0[15], p1[0]);
; #pragma unroll
;     for (int r = 1; r < 15; r += 2) pmax = max3f(pmax, p1[r], p1[r + 1]);
;     pmax = fmaxf(pmax, p1[15]);
;     { auto rr = __builtin_amdgcn_permlane32_swap(__float_as_uint(pmax), __float_as_uint(pmax), false, false);
;       pmax = fmaxf(__uint_as_float(rr[0]), __uint_as_float(rr[1])); }
;     if (!first && __builtin_expect(__all(pmax <= THR2), 1)) { alpha = 1.f; }
; template <bool MLA>
; __device__ __forceinline__ void attn_core(const bf16_t* __restrict__ Qb, const bf16_t* __restrict__ Kh, const bf16_t* __restrict__ Vh, int seq, char* lds,
;                                           f32x16 (&o)[Cfg<MLA>::NCB], const int wid  , const int g  ) {
;     ...
;     __syncthreads();
;     SLOAD(SE, 0); SLOAD(SO, 64); asm volatile("s_waitcnt vmcnt(0)" ::: "memory");
;     SWRITE(0, 0, SE); SWRITE(SHM_K, SHM_V, SO);
;     SLOAD(SE, 2 * 64); SLOAD(SO, 3 * 64);
;     __syncthreads();
;     { int g_ = g; asm volatile("" : "+s"(g_)); if (g_ == 1) __syncthreads(); }
;     for (int j = 0; j < NT; j += 2) {
;         SBAR(); MSEG(j); SBAR();
;         __syncthreads();
;         SBAR(); VSEG(j);
;         SWAIT(); if (j + 2 < NT) SWRITE(((j + 2) % 3) * SHM_K, ((j + 2) & 3) * SHM_V, SE);
;         if (!(MLA && PROBE_NOLOAD)) { const int tn = (j + 4 < NT) ? j + 4 : NT - 1; SLOAD(SE, tn * 64); } SBAR();
;         __syncthreads();
;         SBAR(); MSEG(j + 1); SBAR();
;         __syncthreads();
;         SBAR(); VSEG(j + 1);
.LBB0_1164:
	s_min_u32 s0, s95, 0x7f
	s_lshl_b32 s0, s0, 16
	s_add_i32 s16, s0, 0x40000
	s_add_u32 s0, s58, s16
	s_addc_u32 s1, s59, 0
	global_load_dwordx4 v[132:135], v200, s[0:1]
	global_load_dwordx4 v[128:131], v202, s[0:1]
	v_lshl_add_u64 v[80:81], v[204:205], 0, s[16:17]
	global_load_dwordx4 v[136:139], v[80:81], off
	s_waitcnt lgkmcnt(0)
	s_barrier
	s_add_i32 s99, s98, 0x2400
	s_cmp_eq_u32 s99, 0x6c00
	s_cselect_b32 s99, 0, s99
	v_add_u32_e32 v84, s99, v218
	ds_read_b128 v[80:83], v84
	ds_read_b128 v[192:195], v84 offset:4608
	ds_read_b128 v[188:191], v84 offset:32
	ds_read_b128 v[196:199], v84 offset:4640
	ds_read_b128 v[220:223], v84 offset:64
	ds_read_b128 v[228:231], v84 offset:4672
	ds_read_b128 v[224:227], v84 offset:96
	ds_read_b128 v[232:235], v84 offset:4704
	s_and_b32 s0, s51, 0x8000
	v_add_u32_e32 v187, s0, v217
	ds_read_b64_tr_b16 v[164:165], v187 offset:0
	ds_read_b64_tr_b16 v[166:167], v187 offset:0x800
	ds_read_b64_tr_b16 v[160:161], v187 offset:0x1000
	ds_read_b64_tr_b16 v[162:163], v187 offset:0x1800
	ds_read_b64_tr_b16 v[156:157], v187 offset:0x2000
	ds_read_b64_tr_b16 v[158:159], v187 offset:0x2800
	ds_read_b64_tr_b16 v[152:153], v187 offset:0x3000
	ds_read_b64_tr_b16 v[154:155], v187 offset:0x3800
	s_waitcnt lgkmcnt(15)
	v_mfma_f32_32x32x16_bf16 v[96:111], v[80:83], v[112:115], v[64:79]
	s_waitcnt lgkmcnt(14)
	v_mfma_f32_32x32x16_bf16 v[80:95], v[192:195], v[112:115], v[64:79]
	s_waitcnt lgkmcnt(13)
	v_mfma_f32_32x32x16_bf16 v[96:111], v[188:191], v[116:119], v[96:111]
	s_waitcnt lgkmcnt(12)
	v_mfma_f32_32x32x16_bf16 v[80:95], v[196:199], v[116:119], v[80:95]
	s_waitcnt lgkmcnt(8)
	ds_read_b64_tr_b16 v[188:189], v187 offset:0x200
	ds_read_b64_tr_b16 v[190:191], v187 offset:0xa00
	ds_read_b64_tr_b16 v[192:193], v187 offset:0x1200
	ds_read_b64_tr_b16 v[194:195], v187 offset:0x1a00
	ds_read_b64_tr_b16 v[196:197], v187 offset:0x2200
	ds_read_b64_tr_b16 v[198:199], v187 offset:0x2a00
	ds_read_b64_tr_b16 v[236:237], v187 offset:0x3200
	ds_read_b64_tr_b16 v[238:239], v187 offset:0x3a00
	v_mfma_f32_32x32x16_bf16 v[96:111], v[220:223], v[120:123], v[96:111]
	v_mfma_f32_32x32x16_bf16 v[80:95], v[228:231], v[120:123], v[80:95]
	v_mfma_f32_32x32x16_bf16 v[96:111], v[224:227], v[124:127], v[96:111]
	v_mfma_f32_32x32x16_bf16 v[80:95], v[232:235], v[124:127], v[80:95]
	ds_read_b64_tr_b16 v[220:221], v187 offset:0x600
	ds_read_b64_tr_b16 v[222:223], v187 offset:0xe00
	ds_read_b64_tr_b16 v[224:225], v187 offset:0x1600
	ds_read_b64_tr_b16 v[226:227], v187 offset:0x1e00
	ds_read_b64_tr_b16 v[228:229], v187 offset:0x2600
	ds_read_b64_tr_b16 v[230:231], v187 offset:0x2e00
	ds_read_b64_tr_b16 v[232:233], v187 offset:0x3600
	ds_read_b64_tr_b16 v[234:235], v187 offset:0x3e00
	s_waitcnt lgkmcnt(15)
	v_mfma_f32_32x32x16_bf16 v[48:63], v[180:183], v[164:167], v[48:63]
	v_mfma_f32_32x32x16_bf16 v[48:63], v[176:179], v[160:163], v[48:63]
	v_mfma_f32_32x32x16_bf16 v[48:63], v[172:175], v[156:159], v[48:63]
	v_mfma_f32_32x32x16_bf16 v[48:63], v[168:171], v[152:155], v[48:63]
	ds_read_b64_tr_b16 v[164:165], v187 offset:0x400
	ds_read_b64_tr_b16 v[166:167], v187 offset:0xc00
	ds_read_b64_tr_b16 v[160:161], v187 offset:0x1400
	ds_read_b64_tr_b16 v[162:163], v187 offset:0x1c00
	ds_read_b64_tr_b16 v[156:157], v187 offset:0x2400
	ds_read_b64_tr_b16 v[158:159], v187 offset:0x2c00
	ds_read_b64_tr_b16 v[152:153], v187 offset:0x3400
	ds_read_b64_tr_b16 v[154:155], v187 offset:0x3c00
	s_waitcnt lgkmcnt(15)
	v_mfma_f32_32x32x16_bf16 v[32:47], v[180:183], v[188:191], v[32:47]
	v_mfma_f32_32x32x16_bf16 v[32:47], v[176:179], v[192:195], v[32:47]
	v_mfma_f32_32x32x16_bf16 v[32:47], v[172:175], v[196:199], v[32:47]
	v_mfma_f32_32x32x16_bf16 v[32:47], v[168:171], v[236:239], v[32:47]
	s_waitcnt lgkmcnt(8)
	v_mfma_f32_32x32x16_bf16 v[0:15], v[180:183], v[220:223], v[0:15]
	v_mfma_f32_32x32x16_bf16 v[0:15], v[176:179], v[224:227], v[0:15]
	v_mfma_f32_32x32x16_bf16 v[0:15], v[172:175], v[228:231], v[0:15]
	v_mfma_f32_32x32x16_bf16 v[0:15], v[168:171], v[232:235], v[0:15]
	s_waitcnt lgkmcnt(0)
	v_mfma_f32_32x32x16_bf16 v[16:31], v[180:183], v[164:167], v[16:31]
	v_mfma_f32_32x32x16_bf16 v[16:31], v[176:179], v[160:163], v[16:31]
	v_mfma_f32_32x32x16_bf16 v[16:31], v[172:175], v[156:159], v[16:31]
	v_mfma_f32_32x32x16_bf16 v[16:31], v[168:171], v[152:155], v[16:31]
	s_barrier
	v_max3_f32 v168, v96, v97, v98
	v_exp_f32_e32 v240, v96
	v_max3_f32 v169, v81, v82, v83
	v_exp_f32_e32 v241, v97
	v_max3_f32 v168, v168, v99, v100
	v_exp_f32_e32 v242, v98
	v_max3_f32 v169, v169, v84, v85
	v_exp_f32_e32 v243, v99
	v_max3_f32 v168, v168, v101, v102
	v_exp_f32_e32 v244, v100
	v_max3_f32 v169, v169, v86, v87
	v_exp_f32_e32 v245, v101
	v_max3_f32 v168, v168, v103, v104
	v_exp_f32_e32 v246, v102
	v_max3_f32 v169, v169, v88, v89
	v_exp_f32_e32 v247, v103
	v_max3_f32 v168, v168, v105, v106
	v_exp_f32_e32 v248, v104
	v_max3_f32 v169, v169, v90, v91
	v_exp_f32_e32 v249, v105
	v_max3_f32 v168, v168, v107, v108
	v_exp_f32_e32 v250, v106
	v_max3_f32 v169, v169, v92, v93
	v_exp_f32_e32 v251, v107
	v_max3_f32 v168, v168, v109, v110
	v_exp_f32_e32 v252, v108
	v_max3_f32 v169, v169, v94, v95
	v_exp_f32_e32 v253, v109
	v_max3_f32 v168, v168, v111, v80
	v_exp_f32_e32 v236, v110
	v_max_f32_e32 v168, v168, v169
	v_exp_f32_e32 v237, v111
	v_mov_b32_e32 v169, v168
	s_nop 1
	v_permlane32_swap_b32_e32 v168, v169
	v_max_f32_e32 v168, v168, v169
	v_cmp_ge_f32_e32 vcc, s83, v168
	v_mov_b32_e32 v187, 1.0
	s_cmp_eq_u64 vcc, exec
	s_cbranch_scc1 .Lsp_do0
	s_branch .LBB0_1171

.LBB0_1181:
	s_add_i32 s64, s7, -3
	s_add_i32 s98, s99, 0x2400
	s_cmp_eq_u32 s98, 0x6c00
	s_cselect_b32 s98, 0, s98
	v_add_u32_e32 v84, s98, v218
	ds_read_b128 v[80:83], v84
	ds_read_b128 v[224:227], v84 offset:4608
	ds_read_b128 v[220:223], v84 offset:32
	ds_read_b128 v[228:231], v84 offset:4640
	ds_read_b128 v[192:195], v84 offset:64
	ds_read_b128 v[196:199], v84 offset:4672
	ds_read_b128 v[184:187], v84 offset:96
	ds_read_b128 v[188:191], v84 offset:4704
	s_add_i32 s1, s51, 0xc000
	s_and_b32 s65, s1, 0xc000
	v_add_u32_e32 v236, s65, v217
	s_cmp_eq_u32 s51, 0
	s_cselect_b64 s[60:61], -1, 0
	ds_read_b64_tr_b16 v[164:165], v236 offset:0
	ds_read_b64_tr_b16 v[166:167], v236 offset:0x800
	ds_read_b64_tr_b16 v[160:161], v236 offset:0x1000
	ds_read_b64_tr_b16 v[162:163], v236 offset:0x1800
	ds_read_b64_tr_b16 v[156:157], v236 offset:0x2000
	ds_read_b64_tr_b16 v[158:159], v236 offset:0x2800
	ds_read_b64_tr_b16 v[152:153], v236 offset:0x3000
	ds_read_b64_tr_b16 v[154:155], v236 offset:0x3800
	s_waitcnt lgkmcnt(15)
	v_mfma_f32_32x32x16_bf16 v[96:111], v[80:83], v[112:115], v[64:79]
	s_waitcnt lgkmcnt(14)
	v_mfma_f32_32x32x16_bf16 v[80:95], v[224:227], v[112:115], v[64:79]
	s_waitcnt lgkmcnt(13)
	v_mfma_f32_32x32x16_bf16 v[96:111], v[220:223], v[116:119], v[96:111]
	s_waitcnt lgkmcnt(12)
	v_mfma_f32_32x32x16_bf16 v[80:95], v[228:231], v[116:119], v[80:95]
	s_waitcnt lgkmcnt(8)
	ds_read_b64_tr_b16 v[220:221], v236 offset:0x200
	ds_read_b64_tr_b16 v[222:223], v236 offset:0xa00
	ds_read_b64_tr_b16 v[224:225], v236 offset:0x1200
	ds_read_b64_tr_b16 v[226:227], v236 offset:0x1a00
	ds_read_b64_tr_b16 v[228:229], v236 offset:0x2200
	ds_read_b64_tr_b16 v[230:231], v236 offset:0x2a00
	ds_read_b64_tr_b16 v[232:233], v236 offset:0x3200
	ds_read_b64_tr_b16 v[234:235], v236 offset:0x3a00
	v_mfma_f32_32x32x16_bf16 v[96:111], v[192:195], v[120:123], v[96:111]
	v_mfma_f32_32x32x16_bf16 v[80:95], v[196:199], v[120:123], v[80:95]
	v_mfma_f32_32x32x16_bf16 v[96:111], v[184:187], v[124:127], v[96:111]
	v_mfma_f32_32x32x16_bf16 v[80:95], v[188:191], v[124:127], v[80:95]
	ds_read_b64_tr_b16 v[184:185], v236 offset:0x600
	ds_read_b64_tr_b16 v[186:187], v236 offset:0xe00
	ds_read_b64_tr_b16 v[188:189], v236 offset:0x1600
	ds_read_b64_tr_b16 v[190:191], v236 offset:0x1e00
	ds_read_b64_tr_b16 v[192:193], v236 offset:0x2600
	ds_read_b64_tr_b16 v[194:195], v236 offset:0x2e00
	ds_read_b64_tr_b16 v[196:197], v236 offset:0x3600
	ds_read_b64_tr_b16 v[198:199], v236 offset:0x3e00
	s_and_b64 vcc, exec, s[60:61]
	s_cbranch_vccnz .Ld1_b_nopv
	s_waitcnt lgkmcnt(15)
	v_mfma_f32_32x32x16_bf16 v[48:63], v[180:183], v[164:167], v[48:63]
	v_mfma_f32_32x32x16_bf16 v[48:63], v[176:179], v[160:163], v[48:63]
	v_mfma_f32_32x32x16_bf16 v[48:63], v[172:175], v[156:159], v[48:63]
	v_mfma_f32_32x32x16_bf16 v[48:63], v[168:171], v[152:155], v[48:63]
	ds_read_b64_tr_b16 v[164:165], v236 offset:0x400
	ds_read_b64_tr_b16 v[166:167], v236 offset:0xc00
	ds_read_b64_tr_b16 v[160:161], v236 offset:0x1400
	ds_read_b64_tr_b16 v[162:163], v236 offset:0x1c00
	ds_read_b64_tr_b16 v[156:157], v236 offset:0x2400
	ds_read_b64_tr_b16 v[158:159], v236 offset:0x2c00
	ds_read_b64_tr_b16 v[152:153], v236 offset:0x3400
	ds_read_b64_tr_b16 v[154:155], v236 offset:0x3c00
	s_waitcnt lgkmcnt(15)
	v_mfma_f32_32x32x16_bf16 v[32:47], v[180:183], v[220:223], v[32:47]
	v_mfma_f32_32x32x16_bf16 v[32:47], v[176:179], v[224:227], v[32:47]
	v_mfma_f32_32x32x16_bf16 v[32:47], v[172:175], v[228:231], v[32:47]
	v_mfma_f32_32x32x16_bf16 v[32:47], v[168:171], v[232:235], v[32:47]
	s_waitcnt lgkmcnt(8)
	v_mfma_f32_32x32x16_bf16 v[0:15], v[180:183], v[184:187], v[0:15]
	v_mfma_f32_32x32x16_bf16 v[0:15], v[176:179], v[188:191], v[0:15]
	v_mfma_f32_32x32x16_bf16 v[0:15], v[172:175], v[192:195], v[0:15]
	v_mfma_f32_32x32x16_bf16 v[0:15], v[168:171], v[196:199], v[0:15]
	s_waitcnt lgkmcnt(0)
	v_mfma_f32_32x32x16_bf16 v[16:31], v[180:183], v[164:167], v[16:31]
	v_mfma_f32_32x32x16_bf16 v[16:31], v[176:179], v[160:163], v[16:31]
	v_mfma_f32_32x32x16_bf16 v[16:31], v[172:175], v[156:159], v[16:31]
	v_mfma_f32_32x32x16_bf16 v[16:31], v[168:171], v[152:155], v[16:31]

; #define SBAR() __builtin_amdgcn_sched_barrier(0)
; __device__ __forceinline__ float max3f(float a, float b, float c) { return __builtin_fmaxf(__builtin_fmaxf(a, b), c); }
; #define SWAIT() asm volatile("s_waitcnt vmcnt(3)" ::: "memory")
; #define VSEG(j) do { rowmax_adjust(S0, S1, m2, negm, alpha, (j) == 0); RESC(alpha); l_reg = l_reg * alpha + exp_pack(S0, S1, pa0, pa1, pa2, pa3); } while (0)
; __device__ __forceinline__ void rowmax_adjust(f32x16& p0, f32x16& p1, float& m2, f32x16& negm, float& alpha, const bool first) {
;     constexpr float THR2 = THR * 1.4426950408889634f;
;     float pmax = max3f(p0[0], p0[1], p0[2]);
; #pragma unroll
;     for (int r = 3; r < 15; r += 2) pmax = max3f(pmax, p0[r], p0[r + 1]);
;     pmax = max3f(pmax, p0[15], p1[0]);
; #pragma unroll
;     for (int r = 1; r < 15; r += 2) pmax = max3f(pmax, p1[r], p1[r + 1]);
;     pmax = fmaxf(pmax, p1[15]);
;     { auto rr = __builtin_amdgcn_permlane32_swap(__float_as_uint(pmax), __float_as_uint(pmax), false, false);
;       pmax = fmaxf(__uint_as_float(rr[0]), __uint_as_float(rr[1])); }
;     if (!first && __builtin_expect(__all(pmax <= THR2), 1)) { alpha = 1.f; }
; template <bool MLA>
; __device__ __forceinline__ void attn_core(const bf16_t* __restrict__ Qb, const bf16_t* __restrict__ Kh, const bf16_t* __restrict__ Vh, int seq, char* lds,
;                                           f32x16 (&o)[Cfg<MLA>::NCB], const int wid  , const int g  ) {
;     ...
;     __syncthreads();
;     SLOAD(SE, 0); SLOAD(SO, 64); asm volatile("s_waitcnt vmcnt(0)" ::: "memory");
;     SWRITE(0, 0, SE); SWRITE(SHM_K, SHM_V, SO);
;     SLOAD(SE, 2 * 64); SLOAD(SO, 3 * 64);
;     __syncthreads();
;     { int g_ = g; asm volatile("" : "+s"(g_)); if (g_ == 1) __syncthreads(); }
;     for (int j = 0; j < NT; j += 2) {
;         SBAR(); MSEG(j); SBAR();
;         __syncthreads();
;         SBAR(); VSEG(j);
;         SWAIT(); if (j + 2 < NT) SWRITE(((j + 2) % 3) * SHM_K, ((j + 2) & 3) * SHM_V, SE);
;         if (!(MLA && PROBE_NOLOAD)) { const int tn = (j + 4 < NT) ? j + 4 : NT - 1; SLOAD(SE, tn * 64); } SBAR();
;         __syncthreads();
;         SBAR(); MSEG(j + 1); SBAR();
;         __syncthreads();
;         SBAR(); VSEG(j + 1);
.LBB0_1195:
	s_min_u32 s0, s64, 0x7f
	s_lshl_b32 s0, s0, 16
	s_add_i32 s16, s0, 0x40000
	s_add_u32 s0, s58, s16
	s_addc_u32 s1, s59, 0
	global_load_dwordx4 v[132:135], v200, s[0:1]
	global_load_dwordx4 v[128:131], v202, s[0:1]
	v_lshl_add_u64 v[80:81], v[204:205], 0, s[16:17]
	global_load_dwordx4 v[136:139], v[80:81], off
	s_waitcnt lgkmcnt(0)
	s_barrier
	s_add_i32 s99, s98, 0x2400
	s_cmp_eq_u32 s99, 0x6c00
	s_cselect_b32 s99, 0, s99
	v_add_u32_e32 v84, s99, v218
	ds_read_b128 v[80:83], v84
	ds_read_b128 v[192:195], v84 offset:4608
	ds_read_b128 v[188:191], v84 offset:32
	ds_read_b128 v[196:199], v84 offset:4640
	ds_read_b128 v[220:223], v84 offset:64
	ds_read_b128 v[228:231], v84 offset:4672
	ds_read_b128 v[224:227], v84 offset:96
	ds_read_b128 v[232:235], v84 offset:4704
	s_and_b32 s0, s51, 0x8000
	v_add_u32_e32 v187, s0, v217
	ds_read_b64_tr_b16 v[164:165], v187 offset:0
	ds_read_b64_tr_b16 v[166:167], v187 offset:0x800
	ds_read_b64_tr_b16 v[160:161], v187 offset:0x1000
	ds_read_b64_tr_b16 v[162:163], v187 offset:0x1800
	ds_read_b64_tr_b16 v[156:157], v187 offset:0x2000
	ds_read_b64_tr_b16 v[158:159], v187 offset:0x2800
	ds_read_b64_tr_b16 v[152:153], v187 offset:0x3000
	ds_read_b64_tr_b16 v[154:155], v187 offset:0x3800
	s_waitcnt lgkmcnt(15)
	v_mfma_f32_32x32x16_bf16 v[96:111], v[80:83], v[112:115], v[64:79]
	s_waitcnt lgkmcnt(14)
	v_mfma_f32_32x32x16_bf16 v[80:95], v[192:195], v[112:115], v[64:79]
	s_waitcnt lgkmcnt(13)
	v_mfma_f32_32x32x16_bf16 v[96:111], v[188:191], v[116:119], v[96:111]
	s_waitcnt lgkmcnt(12)
	v_mfma_f32_32x32x16_bf16 v[80:95], v[196:199], v[116:119], v[80:95]
	s_waitcnt lgkmcnt(8)
	ds_read_b64_tr_b16 v[188:189], v187 offset:0x200
	ds_read_b64_tr_b16 v[190:191], v187 offset:0xa00
	ds_read_b64_tr_b16 v[192:193], v187 offset:0x1200
	ds_read_b64_tr_b16 v[194:195], v187 offset:0x1a00
	ds_read_b64_tr_b16 v[196:197], v187 offset:0x2200
	ds_read_b64_tr_b16 v[198:199], v187 offset:0x2a00
	ds_read_b64_tr_b16 v[236:237], v187 offset:0x3200
	ds_read_b64_tr_b16 v[238:239], v187 offset:0x3a00
	v_mfma_f32_32x32x16_bf16 v[96:111], v[220:223], v[120:123], v[96:111]
	v_mfma_f32_32x32x16_bf16 v[80:95], v[228:231], v[120:123], v[80:95]
	v_mfma_f32_32x32x16_bf16 v[96:111], v[224:227], v[124:127], v[96:111]
	v_mfma_f32_32x32x16_bf16 v[80:95], v[232:235], v[124:127], v[80:95]
	ds_read_b64_tr_b16 v[220:221], v187 offset:0x600
	ds_read_b64_tr_b16 v[222:223], v187 offset:0xe00
	ds_read_b64_tr_b16 v[224:225], v187 offset:0x1600
	ds_read_b64_tr_b16 v[226:227], v187 offset:0x1e00
	ds_read_b64_tr_b16 v[228:229], v187 offset:0x2600
	ds_read_b64_tr_b16 v[230:231], v187 offset:0x2e00
	ds_read_b64_tr_b16 v[232:233], v187 offset:0x3600
	ds_read_b64_tr_b16 v[234:235], v187 offset:0x3e00
	s_waitcnt lgkmcnt(15)
	v_mfma_f32_32x32x16_bf16 v[48:63], v[180:183], v[164:167], v[48:63]
	v_mfma_f32_32x32x16_bf16 v[48:63], v[176:179], v[160:163], v[48:63]
	v_mfma_f32_32x32x16_bf16 v[48:63], v[172:175], v[156:159], v[48:63]
	v_mfma_f32_32x32x16_bf16 v[48:63], v[168:171], v[152:155], v[48:63]
	ds_read_b64_tr_b16 v[164:165], v187 offset:0x400
	ds_read_b64_tr_b16 v[166:167], v187 offset:0xc00
	ds_read_b64_tr_b16 v[160:161], v187 offset:0x1400
	ds_read_b64_tr_b16 v[162:163], v187 offset:0x1c00
	ds_read_b64_tr_b16 v[156:157], v187 offset:0x2400
	ds_read_b64_tr_b16 v[158:159], v187 offset:0x2c00
	ds_read_b64_tr_b16 v[152:153], v187 offset:0x3400
	ds_read_b64_tr_b16 v[154:155], v187 offset:0x3c00
	s_waitcnt lgkmcnt(15)
	v_mfma_f32_32x32x16_bf16 v[32:47], v[180:183], v[188:191], v[32:47]
	v_mfma_f32_32x32x16_bf16 v[32:47], v[176:179], v[192:195], v[32:47]
	v_mfma_f32_32x32x16_bf16 v[32:47], v[172:175], v[196:199], v[32:47]
	v_mfma_f32_32x32x16_bf16 v[32:47], v[168:171], v[236:239], v[32:47]
	s_waitcnt lgkmcnt(8)
	v_mfma_f32_32x32x16_bf16 v[0:15], v[180:183], v[220:223], v[0:15]
	v_mfma_f32_32x32x16_bf16 v[0:15], v[176:179], v[224:227], v[0:15]
	v_mfma_f32_32x32x16_bf16 v[0:15], v[172:175], v[228:231], v[0:15]
	v_mfma_f32_32x32x16_bf16 v[0:15], v[168:171], v[232:235], v[0:15]
	s_waitcnt lgkmcnt(0)
	v_mfma_f32_32x32x16_bf16 v[16:31], v[180:183], v[164:167], v[16:31]
	v_mfma_f32_32x32x16_bf16 v[16:31], v[176:179], v[160:163], v[16:31]
	v_mfma_f32_32x32x16_bf16 v[16:31], v[172:175], v[156:159], v[16:31]
	v_mfma_f32_32x32x16_bf16 v[16:31], v[168:171], v[152:155], v[16:31]
	s_barrier
	v_max3_f32 v168, v96, v97, v98
	v_exp_f32_e32 v240, v96
	v_max3_f32 v169, v81, v82, v83
	v_exp_f32_e32 v241, v97
	v_max3_f32 v168, v168, v99, v100
	v_exp_f32_e32 v242, v98
	v_max3_f32 v169, v169, v84, v85
	v_exp_f32_e32 v243, v99
	v_max3_f32 v168, v168, v101, v102
	v_exp_f32_e32 v244, v100
	v_max3_f32 v169, v169, v86, v87
	v_exp_f32_e32 v245, v101
	v_max3_f32 v168, v168, v103, v104
	v_exp_f32_e32 v246, v102
	v_max3_f32 v169, v169, v88, v89
	v_exp_f32_e32 v247, v103
	v_max3_f32 v168, v168, v105, v106
	v_exp_f32_e32 v248, v104
	v_max3_f32 v169, v169, v90, v91
	v_exp_f32_e32 v249, v105
	v_max3_f32 v168, v168, v107, v108
	v_exp_f32_e32 v250, v106
	v_max3_f32 v169, v169, v92, v93
	v_exp_f32_e32 v251, v107
	v_max3_f32 v168, v168, v109, v110
	v_exp_f32_e32 v252, v108
	v_max3_f32 v169, v169, v94, v95
	v_exp_f32_e32 v253, v109
	v_max3_f32 v168, v168, v111, v80
	v_exp_f32_e32 v236, v110
	v_max_f32_e32 v168, v168, v169
	v_exp_f32_e32 v237, v111
	v_mov_b32_e32 v169, v168
	s_nop 1
	v_permlane32_swap_b32_e32 v168, v169
	v_max_f32_e32 v168, v168, v169
	v_cmp_ge_f32_e32 vcc, s83, v168
	v_mov_b32_e32 v187, 1.0
	s_cmp_eq_u64 vcc, exec
	s_cbranch_scc1 .Lsp_do31
	s_branch .LBB0_1202
